# strategy 4 in the epilogue: leading half runs its SwiGLU epilogue at priority 2 so its next-unit load segment overlaps the trailing half's epilogue
# baseline (speedup 1.0000x reference)
;     DI void operator()(const f32x4 (&acc)[2][2][4][2], const pg8::Unit& u, int wr, int wc, int fr, int fq) const {
;         const int row0 = u.pm * 256 + wr * 64 + fr, col0 = u.pn * 128 + wc * 32 + 8 * fq;
;         float rs[2][4]; row_rstd(ssq, row0, fq, rs);
; #pragma unroll
;         for (int ai = 0; ai < 2; ++ai)
; #pragma unroll
;             for (int m = 0; m < 4; ++m) {
;                 typedef float f32x2 __attribute__((ext_vector_type(2)));
;                 const float r = rs[ai][m]; const float r2s = r * r, rls = r * -1.44269504f; const f32x2 r2 = {r2s, r2s}, rl = {rls, rls};
;                 unsigned hw[4];
; #pragma unroll
;                 for (int q = 0; q < 4; ++q) {
;                     const f32x4 gq = acc[ai][0][m][q >> 1], uq = acc[ai][1][m][q >> 1];
;                     const f32x2 g2 = {gq[2 * (q & 1)], gq[2 * (q & 1) + 1]}, u2 = {uq[2 * (q & 1)], uq[2 * (q & 1) + 1]};
;                     const f32x2 t = g2 * rl; f32x2 e; e.x = __builtin_amdgcn_exp2f(t.x); e.y = __builtin_amdgcn_exp2f(t.y);
;                     const f32x2 d = e + 1.0f; f32x2 rc; rc.x = __builtin_amdgcn_rcpf(d.x); rc.y = __builtin_amdgcn_rcpf(d.y);
;                     const f32x2 hv = ((g2 * u2) * r2) * rc;
.Lrc_skip_0:
.LBB0_169:
	v_and_b32_e32 v131, 64, v194
	v_xor_b32_e32 v130, 16, v194
	v_add_u32_e32 v131, 64, v131
	v_cmp_lt_i32_e32 vcc, v130, v131
	v_lshl_add_u32 v160, s58, 8, v182
	v_ashrrev_i32_e32 v161, 31, v160
	v_cndmask_b32_e32 v130, v194, v130, vcc
	v_lshlrev_b32_e32 v186, 2, v130
	v_xor_b32_e32 v130, 32, v194
	v_cmp_lt_i32_e32 vcc, v130, v131
	v_or_b32_e32 v158, 16, v160
	v_ashrrev_i32_e32 v159, 31, v158
	v_cndmask_b32_e32 v130, v194, v130, vcc
	v_lshlrev_b32_e32 v163, 2, v130
	v_lshlrev_b64 v[130:131], 6, v[160:161]
	v_lshl_add_u64 v[130:131], v[140:141], 0, v[130:131]
	v_mov_b64_e32 v[178:179], s[16:17]
	v_or_b32_e32 v156, 32, v160
	v_ashrrev_i32_e32 v157, 31, v156
	v_or_b32_e32 v154, 48, v160
	v_ashrrev_i32_e32 v155, 31, v154
	v_add_u32_e32 v152, 0x80, v160
	v_ashrrev_i32_e32 v153, 31, v152
	v_add_u32_e32 v150, 0x90, v160
	v_ashrrev_i32_e32 v151, 31, v150
	v_pk_mul_f32 v[122:123], v[126:127], v[122:123]
	v_pk_mul_f32 v[124:125], v[128:129], v[124:125]
	v_pk_mul_f32 v[114:115], v[118:119], v[114:115]
	v_pk_mul_f32 v[116:117], v[120:121], v[116:117]
	v_lshl_or_b32 v162, s57, 7, v184
	v_pk_mul_f32 v[106:107], v[110:111], v[106:107]
	v_pk_mul_f32 v[108:109], v[112:113], v[108:109]
	v_pk_mul_f32 v[98:99], v[102:103], v[98:99]
	v_pk_mul_f32 v[100:101], v[104:105], v[100:101]
	v_pk_mul_f32 v[90:91], v[94:95], v[90:91]
	v_pk_mul_f32 v[92:93], v[96:97], v[92:93]
	v_pk_mul_f32 v[82:83], v[86:87], v[82:83]
	v_pk_mul_f32 v[84:85], v[88:89], v[84:85]
	v_pk_mul_f32 v[74:75], v[78:79], v[74:75]
	v_pk_mul_f32 v[76:77], v[80:81], v[76:77]
	v_pk_mul_f32 v[66:67], v[70:71], v[66:67]
	v_pk_mul_f32 v[68:69], v[72:73], v[68:69]
	v_pk_mul_f32 v[58:59], v[62:63], v[58:59]
	v_pk_mul_f32 v[60:61], v[64:65], v[60:61]
	v_pk_mul_f32 v[50:51], v[54:55], v[50:51]
	v_pk_mul_f32 v[52:53], v[56:57], v[52:53]
	v_pk_mul_f32 v[42:43], v[46:47], v[42:43]
	v_pk_mul_f32 v[44:45], v[48:49], v[44:45]
	v_pk_mul_f32 v[34:35], v[38:39], v[34:35]
	v_pk_mul_f32 v[36:37], v[40:41], v[36:37]
	v_pk_mul_f32 v[26:27], v[30:31], v[26:27]
	v_pk_mul_f32 v[28:29], v[32:33], v[28:29]
	v_pk_mul_f32 v[18:19], v[22:23], v[18:19]
	v_pk_mul_f32 v[20:21], v[24:25], v[20:21]
	v_pk_mul_f32 v[10:11], v[14:15], v[10:11]
	v_pk_mul_f32 v[12:13], v[16:17], v[12:13]
	v_pk_mul_f32 v[2:3], v[6:7], v[2:3]
	v_pk_mul_f32 v[4:5], v[8:9], v[4:5]
	s_and_b64 vcc, exec, s[42:43]
	s_cbranch_vccz .Lab_0
	s_barrier
	s_setprio 2

; DI unsigned pk2(float lo, float hi) { return pg8::cvt_pk_bf16(lo, hi); }
;     DI void operator()(const f32x4 (&acc)[2][2][4][2], const pg8::Unit& u, int wr, int wc, int fr, int fq) const {
;     ...
;                 const float r = rs[ai][m]; const float r2s = r * r, rls = r * -1.44269504f; const f32x2 r2 = {r2s, r2s}, rl = {rls, rls};
;                 unsigned hw[4];
; #pragma unroll
;                 for (int q = 0; q < 4; ++q) {
;                     const f32x4 gq = acc[ai][0][m][q >> 1], uq = acc[ai][1][m][q >> 1];
;                     const f32x2 g2 = {gq[2 * (q & 1)], gq[2 * (q & 1) + 1]}, u2 = {uq[2 * (q & 1)], uq[2 * (q & 1) + 1]};
;                     const f32x2 t = g2 * rl; f32x2 e; e.x = __builtin_amdgcn_exp2f(t.x); e.y = __builtin_amdgcn_exp2f(t.y);
;                     const f32x2 d = e + 1.0f; f32x2 rc; rc.x = __builtin_amdgcn_rcpf(d.x); rc.y = __builtin_amdgcn_rcpf(d.y);
;                     const f32x2 hv = ((g2 * u2) * r2) * rc;
;                     hw[q] = pk2(hv.x, hv.y);
;                 }
;                 u32x4 w; w.x = hw[0]; w.y = hw[1]; w.z = hw[2]; w.w = hw[3];
;                 *(u32x4*)(H + (size_t)(row0 + ai * 128 + m * 16) * DFF + col0) = w;
.Lrc_done_0:
	v_mov_b64_e32 v[236:237], s[84:85]
	v_lshlrev_b64 v[180:181], 1, v[162:163]
	v_mul_f32_e32 v178, 0xbfb8aa3b, v161
	v_pk_mul_f32 v[126:127], v[126:127], v[178:179] op_sel_hi:[1,0]
	v_mul_f32_e32 v132, v161, v161
	v_pk_mul_f32 v[122:123], v[122:123], v[132:133] op_sel_hi:[1,0]
	v_exp_f32_e32 v126, v126
	v_pk_mul_f32 v[128:129], v[128:129], v[178:179] op_sel_hi:[1,0]
	v_exp_f32_e32 v127, v127
	s_nop 0
	v_pk_add_f32 v[126:127], v[126:127], 1.0 op_sel_hi:[1,0]
	v_pk_mul_f32 v[124:125], v[124:125], v[132:133] op_sel_hi:[1,0]
	v_exp_f32_e32 v128, v128
	v_pk_mul_f32 v[118:119], v[118:119], v[178:179] op_sel_hi:[1,0]
	v_exp_f32_e32 v129, v129
	v_rcp_f32_e32 v126, v126
	v_pk_add_f32 v[128:129], v[128:129], 1.0 op_sel_hi:[1,0]
	v_rcp_f32_e32 v127, v127
	v_pk_mul_f32 v[114:115], v[114:115], v[132:133] op_sel_hi:[1,0]
	v_exp_f32_e32 v118, v118
	v_pk_mul_f32 v[120:121], v[120:121], v[178:179] op_sel_hi:[1,0]
	v_exp_f32_e32 v119, v119
	v_pk_mul_f32 v[122:123], v[122:123], v[126:127]
	v_rcp_f32_e32 v128, v128
	v_pk_add_f32 v[118:119], v[118:119], 1.0 op_sel_hi:[1,0]
	v_rcp_f32_e32 v129, v129
	v_pk_mul_f32 v[116:117], v[116:117], v[132:133] op_sel_hi:[1,0]
	v_exp_f32_e32 v120, v120
	v_mul_f32_e32 v190, 0xbfb8aa3b, v159
	v_pk_mul_f32 v[110:111], v[110:111], v[190:191] op_sel_hi:[1,0]
	v_exp_f32_e32 v121, v121
	v_cvt_pk_bf16_f32 v126, v122, v123
	v_pk_mul_f32 v[124:125], v[124:125], v[128:129]
	v_rcp_f32_e32 v118, v118
	v_pk_add_f32 v[120:121], v[120:121], 1.0 op_sel_hi:[1,0]
	v_rcp_f32_e32 v119, v119
	v_mul_f32_e32 v234, v159, v159
	v_pk_mul_f32 v[106:107], v[106:107], v[234:235] op_sel_hi:[1,0]
	v_exp_f32_e32 v110, v110
	v_pk_mul_f32 v[112:113], v[112:113], v[190:191] op_sel_hi:[1,0]
	v_exp_f32_e32 v111, v111
	v_cvt_pk_bf16_f32 v127, v124, v125
	v_pk_mul_f32 v[114:115], v[114:115], v[118:119]
	v_rcp_f32_e32 v120, v120
	v_pk_add_f32 v[110:111], v[110:111], 1.0 op_sel_hi:[1,0]
	v_rcp_f32_e32 v121, v121
	v_pk_mul_f32 v[108:109], v[108:109], v[234:235] op_sel_hi:[1,0]
	v_exp_f32_e32 v112, v112
	v_pk_mul_f32 v[102:103], v[102:103], v[190:191] op_sel_hi:[1,0]
	v_exp_f32_e32 v113, v113
	v_cvt_pk_bf16_f32 v128, v114, v115
	v_pk_mul_f32 v[116:117], v[116:117], v[120:121]
	v_rcp_f32_e32 v110, v110
	v_pk_add_f32 v[112:113], v[112:113], 1.0 op_sel_hi:[1,0]
	v_rcp_f32_e32 v111, v111
	v_pk_mul_f32 v[98:99], v[98:99], v[234:235] op_sel_hi:[1,0]
	v_exp_f32_e32 v102, v102
	v_pk_mul_f32 v[104:105], v[104:105], v[190:191] op_sel_hi:[1,0]
	v_exp_f32_e32 v103, v103
	v_cvt_pk_bf16_f32 v129, v116, v117
	v_mad_i64_i32 v[118:119], s[2:3], v160, s27, v[236:237]
	v_lshl_add_u64 v[118:119], v[118:119], 0, v[180:181]
	global_store_dwordx4 v[118:119], v[126:129], off
	v_pk_mul_f32 v[106:107], v[106:107], v[110:111]
	v_rcp_f32_e32 v112, v112
	v_pk_add_f32 v[102:103], v[102:103], 1.0 op_sel_hi:[1,0]
	v_rcp_f32_e32 v113, v113
	v_pk_mul_f32 v[100:101], v[100:101], v[234:235] op_sel_hi:[1,0]
	v_exp_f32_e32 v104, v104
	v_mul_f32_e32 v178, 0xbfb8aa3b, v157
	v_pk_mul_f32 v[94:95], v[94:95], v[178:179] op_sel_hi:[1,0]
	v_exp_f32_e32 v105, v105
	v_cvt_pk_bf16_f32 v110, v106, v107
	v_pk_mul_f32 v[108:109], v[108:109], v[112:113]
	v_rcp_f32_e32 v102, v102
	v_pk_add_f32 v[104:105], v[104:105], 1.0 op_sel_hi:[1,0]
	v_rcp_f32_e32 v103, v103
	v_mul_f32_e32 v132, v157, v157
	v_pk_mul_f32 v[90:91], v[90:91], v[132:133] op_sel_hi:[1,0]
	v_exp_f32_e32 v94, v94
	v_pk_mul_f32 v[96:97], v[96:97], v[178:179] op_sel_hi:[1,0]
	v_exp_f32_e32 v95, v95
	v_cvt_pk_bf16_f32 v111, v108, v109
	v_pk_mul_f32 v[98:99], v[98:99], v[102:103]
	v_rcp_f32_e32 v104, v104
	v_pk_add_f32 v[94:95], v[94:95], 1.0 op_sel_hi:[1,0]
	v_rcp_f32_e32 v105, v105
	v_pk_mul_f32 v[92:93], v[92:93], v[132:133] op_sel_hi:[1,0]
	v_exp_f32_e32 v96, v96
	v_pk_mul_f32 v[86:87], v[86:87], v[178:179] op_sel_hi:[1,0]
	v_exp_f32_e32 v97, v97
	v_cvt_pk_bf16_f32 v112, v98, v99
	v_pk_mul_f32 v[100:101], v[100:101], v[104:105]
	v_rcp_f32_e32 v94, v94
	v_pk_add_f32 v[96:97], v[96:97], 1.0 op_sel_hi:[1,0]
	v_rcp_f32_e32 v95, v95
	v_pk_mul_f32 v[82:83], v[82:83], v[132:133] op_sel_hi:[1,0]
	v_exp_f32_e32 v86, v86
	v_pk_mul_f32 v[88:89], v[88:89], v[178:179] op_sel_hi:[1,0]
	v_exp_f32_e32 v87, v87
	v_cvt_pk_bf16_f32 v113, v100, v101
	v_mad_i64_i32 v[102:103], s[2:3], v158, s27, v[236:237]
	v_lshl_add_u64 v[102:103], v[102:103], 0, v[180:181]
	global_store_dwordx4 v[102:103], v[110:113], off
	v_pk_mul_f32 v[90:91], v[90:91], v[94:95]
	v_rcp_f32_e32 v96, v96
	v_pk_add_f32 v[86:87], v[86:87], 1.0 op_sel_hi:[1,0]
	v_rcp_f32_e32 v97, v97
	v_pk_mul_f32 v[84:85], v[84:85], v[132:133] op_sel_hi:[1,0]
	v_exp_f32_e32 v88, v88
	v_mul_f32_e32 v190, 0xbfb8aa3b, v155
	v_pk_mul_f32 v[78:79], v[78:79], v[190:191] op_sel_hi:[1,0]
	v_exp_f32_e32 v89, v89
	v_cvt_pk_bf16_f32 v94, v90, v91
	v_pk_mul_f32 v[92:93], v[92:93], v[96:97]
	v_rcp_f32_e32 v86, v86
	v_pk_add_f32 v[88:89], v[88:89], 1.0 op_sel_hi:[1,0]
	v_rcp_f32_e32 v87, v87
	v_mul_f32_e32 v234, v155, v155
	v_pk_mul_f32 v[74:75], v[74:75], v[234:235] op_sel_hi:[1,0]
	v_exp_f32_e32 v78, v78
	v_pk_mul_f32 v[80:81], v[80:81], v[190:191] op_sel_hi:[1,0]
	v_exp_f32_e32 v79, v79
	v_cvt_pk_bf16_f32 v95, v92, v93
	v_pk_mul_f32 v[82:83], v[82:83], v[86:87]
	v_rcp_f32_e32 v88, v88
	v_pk_add_f32 v[78:79], v[78:79], 1.0 op_sel_hi:[1,0]
	v_rcp_f32_e32 v89, v89
	v_pk_mul_f32 v[76:77], v[76:77], v[234:235] op_sel_hi:[1,0]
	v_exp_f32_e32 v80, v80
	v_pk_mul_f32 v[70:71], v[70:71], v[190:191] op_sel_hi:[1,0]
	v_exp_f32_e32 v81, v81
	v_cvt_pk_bf16_f32 v96, v82, v83
	v_pk_mul_f32 v[84:85], v[84:85], v[88:89]
	v_rcp_f32_e32 v78, v78
	v_pk_add_f32 v[80:81], v[80:81], 1.0 op_sel_hi:[1,0]
	v_rcp_f32_e32 v79, v79
; DI unsigned pk2(float lo, float hi) { return pg8::cvt_pk_bf16(lo, hi); }
;     DI void operator()(const f32x4 (&acc)[2][2][4][2], const pg8::Unit& u, int wr, int wc, int fr, int fq) const {
;     ...
;                 const float r = rs[ai][m]; const float r2s = r * r, rls = r * -1.44269504f; const f32x2 r2 = {r2s, r2s}, rl = {rls, rls};
;                 unsigned hw[4];
; #pragma unroll
;                 for (int q = 0; q < 4; ++q) {
;                     const f32x4 gq = acc[ai][0][m][q >> 1], uq = acc[ai][1][m][q >> 1];
;                     const f32x2 g2 = {gq[2 * (q & 1)], gq[2 * (q & 1) + 1]}, u2 = {uq[2 * (q & 1)], uq[2 * (q & 1) + 1]};
;                     const f32x2 t = g2 * rl; f32x2 e; e.x = __builtin_amdgcn_exp2f(t.x); e.y = __builtin_amdgcn_exp2f(t.y);
;                     const f32x2 d = e + 1.0f; f32x2 rc; rc.x = __builtin_amdgcn_rcpf(d.x); rc.y = __builtin_amdgcn_rcpf(d.y);
;                     const f32x2 hv = ((g2 * u2) * r2) * rc;
;                     hw[q] = pk2(hv.x, hv.y);
;                 }
;                 u32x4 w; w.x = hw[0]; w.y = hw[1]; w.z = hw[2]; w.w = hw[3];
;                 *(u32x4*)(H + (size_t)(row0 + ai * 128 + m * 16) * DFF + col0) = w;
	v_pk_mul_f32 v[66:67], v[66:67], v[234:235] op_sel_hi:[1,0]
	v_exp_f32_e32 v70, v70
	v_pk_mul_f32 v[72:73], v[72:73], v[190:191] op_sel_hi:[1,0]
	v_exp_f32_e32 v71, v71
	v_cvt_pk_bf16_f32 v97, v84, v85
	v_mad_i64_i32 v[86:87], s[2:3], v156, s27, v[236:237]
	v_lshl_add_u64 v[86:87], v[86:87], 0, v[180:181]
	global_store_dwordx4 v[86:87], v[94:97], off
	v_pk_mul_f32 v[74:75], v[74:75], v[78:79]
	v_rcp_f32_e32 v80, v80
	v_pk_add_f32 v[70:71], v[70:71], 1.0 op_sel_hi:[1,0]
	v_rcp_f32_e32 v81, v81
	v_pk_mul_f32 v[68:69], v[68:69], v[234:235] op_sel_hi:[1,0]
	v_exp_f32_e32 v72, v72
	v_mul_f32_e32 v178, 0xbfb8aa3b, v153
	v_pk_mul_f32 v[62:63], v[62:63], v[178:179] op_sel_hi:[1,0]
	v_exp_f32_e32 v73, v73
	v_cvt_pk_bf16_f32 v78, v74, v75
	v_pk_mul_f32 v[76:77], v[76:77], v[80:81]
	v_rcp_f32_e32 v70, v70
	v_pk_add_f32 v[72:73], v[72:73], 1.0 op_sel_hi:[1,0]
	v_rcp_f32_e32 v71, v71
	v_mul_f32_e32 v132, v153, v153
	v_pk_mul_f32 v[58:59], v[58:59], v[132:133] op_sel_hi:[1,0]
	v_exp_f32_e32 v62, v62
	v_pk_mul_f32 v[64:65], v[64:65], v[178:179] op_sel_hi:[1,0]
	v_exp_f32_e32 v63, v63
	v_cvt_pk_bf16_f32 v79, v76, v77
	v_pk_mul_f32 v[66:67], v[66:67], v[70:71]
	v_rcp_f32_e32 v72, v72
	v_pk_add_f32 v[62:63], v[62:63], 1.0 op_sel_hi:[1,0]
	v_rcp_f32_e32 v73, v73
	v_pk_mul_f32 v[60:61], v[60:61], v[132:133] op_sel_hi:[1,0]
	v_exp_f32_e32 v64, v64
	v_pk_mul_f32 v[54:55], v[54:55], v[178:179] op_sel_hi:[1,0]
	v_exp_f32_e32 v65, v65
	v_cvt_pk_bf16_f32 v80, v66, v67
	v_pk_mul_f32 v[68:69], v[68:69], v[72:73]
	v_rcp_f32_e32 v62, v62
	v_pk_add_f32 v[64:65], v[64:65], 1.0 op_sel_hi:[1,0]
	v_rcp_f32_e32 v63, v63
	v_pk_mul_f32 v[50:51], v[50:51], v[132:133] op_sel_hi:[1,0]
	v_exp_f32_e32 v54, v54
	v_pk_mul_f32 v[56:57], v[56:57], v[178:179] op_sel_hi:[1,0]
	v_exp_f32_e32 v55, v55
	v_cvt_pk_bf16_f32 v81, v68, v69
	v_mad_i64_i32 v[70:71], s[2:3], v154, s27, v[236:237]
	v_lshl_add_u64 v[70:71], v[70:71], 0, v[180:181]
	global_store_dwordx4 v[70:71], v[78:81], off
	v_pk_mul_f32 v[58:59], v[58:59], v[62:63]
	v_rcp_f32_e32 v64, v64
	v_pk_add_f32 v[54:55], v[54:55], 1.0 op_sel_hi:[1,0]
	v_rcp_f32_e32 v65, v65
	v_pk_mul_f32 v[52:53], v[52:53], v[132:133] op_sel_hi:[1,0]
	v_exp_f32_e32 v56, v56
	v_mul_f32_e32 v190, 0xbfb8aa3b, v151
	v_pk_mul_f32 v[46:47], v[46:47], v[190:191] op_sel_hi:[1,0]
	v_exp_f32_e32 v57, v57
	v_cvt_pk_bf16_f32 v62, v58, v59
	v_pk_mul_f32 v[60:61], v[60:61], v[64:65]
	v_rcp_f32_e32 v54, v54
	v_pk_add_f32 v[56:57], v[56:57], 1.0 op_sel_hi:[1,0]
	v_rcp_f32_e32 v55, v55
	v_mul_f32_e32 v234, v151, v151
	v_pk_mul_f32 v[42:43], v[42:43], v[234:235] op_sel_hi:[1,0]
	v_exp_f32_e32 v46, v46
	v_pk_mul_f32 v[48:49], v[48:49], v[190:191] op_sel_hi:[1,0]
	v_exp_f32_e32 v47, v47
	v_cvt_pk_bf16_f32 v63, v60, v61
	v_pk_mul_f32 v[50:51], v[50:51], v[54:55]
	v_rcp_f32_e32 v56, v56
	v_pk_add_f32 v[46:47], v[46:47], 1.0 op_sel_hi:[1,0]
	v_rcp_f32_e32 v57, v57
	v_pk_mul_f32 v[44:45], v[44:45], v[234:235] op_sel_hi:[1,0]
	v_exp_f32_e32 v48, v48
	v_pk_mul_f32 v[38:39], v[38:39], v[190:191] op_sel_hi:[1,0]
	v_exp_f32_e32 v49, v49
	v_cvt_pk_bf16_f32 v64, v50, v51
	v_pk_mul_f32 v[52:53], v[52:53], v[56:57]
	v_rcp_f32_e32 v46, v46
	v_pk_add_f32 v[48:49], v[48:49], 1.0 op_sel_hi:[1,0]
	v_rcp_f32_e32 v47, v47
	v_pk_mul_f32 v[34:35], v[34:35], v[234:235] op_sel_hi:[1,0]
	v_exp_f32_e32 v38, v38
	v_pk_mul_f32 v[40:41], v[40:41], v[190:191] op_sel_hi:[1,0]
	v_exp_f32_e32 v39, v39
	v_cvt_pk_bf16_f32 v65, v52, v53
	v_mad_i64_i32 v[54:55], s[2:3], v152, s27, v[236:237]
	v_lshl_add_u64 v[54:55], v[54:55], 0, v[180:181]
	global_store_dwordx4 v[54:55], v[62:65], off
	v_pk_mul_f32 v[42:43], v[42:43], v[46:47]
	v_rcp_f32_e32 v48, v48
	v_pk_add_f32 v[38:39], v[38:39], 1.0 op_sel_hi:[1,0]
	v_rcp_f32_e32 v49, v49
	v_pk_mul_f32 v[36:37], v[36:37], v[234:235] op_sel_hi:[1,0]
	v_exp_f32_e32 v40, v40
	v_mul_f32_e32 v178, 0xbfb8aa3b, v131
; #define PG8_BAR __builtin_amdgcn_s_barrier()
; DI unsigned pk2(float lo, float hi) { return pg8::cvt_pk_bf16(lo, hi); }
; template <class Epi, class Sched, bool ALIGN_EPI = false, bool SP2 = false>
; __device__ __forceinline__ void gemm_phase(PG8_LAS unsigned char* lds, const Gemm g, const Sched& S, const Epi& E) {
;     ...
;         if (!has_next) break;
; #pragma unroll
;         for (int a = 0; a < 2; ++a)
; #pragma unroll
;             for (int b = 0; b < 2; ++b)
; #pragma unroll
;                 for (int m = 0; m < 4; ++m)
; #pragma unroll
;                     for (int n = 0; n < 2; ++n) acc[a][b][m][n] = (f32x4){0.f, 0.f, 0.f, 0.f};
;         cur = nxt; cA = nA; cB = nB; ++ui;
;         if constexpr (ALIGN_EPI) { if (wr == 1) PG8_BAR; }
;     DI void operator()(const f32x4 (&acc)[2][2][4][2], const pg8::Unit& u, int wr, int wc, int fr, int fq) const {
;     ...
;                 const float r = rs[ai][m]; const float r2s = r * r, rls = r * -1.44269504f; const f32x2 r2 = {r2s, r2s}, rl = {rls, rls};
;                 unsigned hw[4];
; #pragma unroll
;                 for (int q = 0; q < 4; ++q) {
;                     const f32x4 gq = acc[ai][0][m][q >> 1], uq = acc[ai][1][m][q >> 1];
;                     const f32x2 g2 = {gq[2 * (q & 1)], gq[2 * (q & 1) + 1]}, u2 = {uq[2 * (q & 1)], uq[2 * (q & 1) + 1]};
;                     const f32x2 t = g2 * rl; f32x2 e; e.x = __builtin_amdgcn_exp2f(t.x); e.y = __builtin_amdgcn_exp2f(t.y);
;                     const f32x2 d = e + 1.0f; f32x2 rc; rc.x = __builtin_amdgcn_rcpf(d.x); rc.y = __builtin_amdgcn_rcpf(d.y);
;                     const f32x2 hv = ((g2 * u2) * r2) * rc;
;                     hw[q] = pk2(hv.x, hv.y);
;                 }
;                 u32x4 w; w.x = hw[0]; w.y = hw[1]; w.z = hw[2]; w.w = hw[3];
;                 *(u32x4*)(H + (size_t)(row0 + ai * 128 + m * 16) * DFF + col0) = w;
	v_pk_mul_f32 v[30:31], v[30:31], v[178:179] op_sel_hi:[1,0]
	v_exp_f32_e32 v41, v41
	v_cvt_pk_bf16_f32 v46, v42, v43
	v_pk_mul_f32 v[44:45], v[44:45], v[48:49]
	v_rcp_f32_e32 v38, v38
	v_pk_add_f32 v[40:41], v[40:41], 1.0 op_sel_hi:[1,0]
	v_rcp_f32_e32 v39, v39
	v_mul_f32_e32 v132, v131, v131
	v_pk_mul_f32 v[26:27], v[26:27], v[132:133] op_sel_hi:[1,0]
	v_exp_f32_e32 v30, v30
	v_pk_mul_f32 v[32:33], v[32:33], v[178:179] op_sel_hi:[1,0]
	v_exp_f32_e32 v31, v31
	v_cvt_pk_bf16_f32 v47, v44, v45
	v_pk_mul_f32 v[34:35], v[34:35], v[38:39]
	v_rcp_f32_e32 v40, v40
	v_pk_add_f32 v[30:31], v[30:31], 1.0 op_sel_hi:[1,0]
	v_rcp_f32_e32 v41, v41
	v_pk_mul_f32 v[28:29], v[28:29], v[132:133] op_sel_hi:[1,0]
	v_exp_f32_e32 v32, v32
	v_pk_mul_f32 v[22:23], v[22:23], v[178:179] op_sel_hi:[1,0]
	v_exp_f32_e32 v33, v33
	v_cvt_pk_bf16_f32 v48, v34, v35
	v_pk_mul_f32 v[36:37], v[36:37], v[40:41]
	v_rcp_f32_e32 v30, v30
	v_pk_add_f32 v[32:33], v[32:33], 1.0 op_sel_hi:[1,0]
	v_rcp_f32_e32 v31, v31
	v_pk_mul_f32 v[18:19], v[18:19], v[132:133] op_sel_hi:[1,0]
	v_exp_f32_e32 v22, v22
	v_pk_mul_f32 v[24:25], v[24:25], v[178:179] op_sel_hi:[1,0]
	v_exp_f32_e32 v23, v23
	v_cvt_pk_bf16_f32 v49, v36, v37
	v_mad_i64_i32 v[38:39], s[2:3], v150, s27, v[236:237]
	v_lshl_add_u64 v[38:39], v[38:39], 0, v[180:181]
	global_store_dwordx4 v[38:39], v[46:49], off
	v_pk_mul_f32 v[26:27], v[26:27], v[30:31]
	v_rcp_f32_e32 v32, v32
	v_pk_add_f32 v[22:23], v[22:23], 1.0 op_sel_hi:[1,0]
	v_rcp_f32_e32 v33, v33
	v_pk_mul_f32 v[20:21], v[20:21], v[132:133] op_sel_hi:[1,0]
	v_exp_f32_e32 v24, v24
	v_mul_f32_e32 v190, 0xbfb8aa3b, v130
	v_pk_mul_f32 v[14:15], v[14:15], v[190:191] op_sel_hi:[1,0]
	v_exp_f32_e32 v25, v25
	v_cvt_pk_bf16_f32 v30, v26, v27
	v_pk_mul_f32 v[28:29], v[28:29], v[32:33]
	v_rcp_f32_e32 v22, v22
	v_pk_add_f32 v[24:25], v[24:25], 1.0 op_sel_hi:[1,0]
	v_rcp_f32_e32 v23, v23
	v_mul_f32_e32 v234, v130, v130
	v_pk_mul_f32 v[10:11], v[10:11], v[234:235] op_sel_hi:[1,0]
	v_exp_f32_e32 v14, v14
	v_pk_mul_f32 v[16:17], v[16:17], v[190:191] op_sel_hi:[1,0]
	v_exp_f32_e32 v15, v15
	v_cvt_pk_bf16_f32 v31, v28, v29
	v_pk_mul_f32 v[18:19], v[18:19], v[22:23]
	v_rcp_f32_e32 v24, v24
	v_pk_add_f32 v[14:15], v[14:15], 1.0 op_sel_hi:[1,0]
	v_rcp_f32_e32 v25, v25
	v_pk_mul_f32 v[12:13], v[12:13], v[234:235] op_sel_hi:[1,0]
	v_exp_f32_e32 v16, v16
	v_pk_mul_f32 v[6:7], v[6:7], v[190:191] op_sel_hi:[1,0]
	v_exp_f32_e32 v17, v17
	v_cvt_pk_bf16_f32 v32, v18, v19
	v_pk_mul_f32 v[20:21], v[20:21], v[24:25]
	v_rcp_f32_e32 v14, v14
	v_pk_add_f32 v[16:17], v[16:17], 1.0 op_sel_hi:[1,0]
	v_rcp_f32_e32 v15, v15
	v_pk_mul_f32 v[2:3], v[2:3], v[234:235] op_sel_hi:[1,0]
	v_exp_f32_e32 v6, v6
	v_pk_mul_f32 v[8:9], v[8:9], v[190:191] op_sel_hi:[1,0]
	v_exp_f32_e32 v7, v7
	v_cvt_pk_bf16_f32 v33, v20, v21
	v_mad_i64_i32 v[22:23], s[2:3], v148, s27, v[236:237]
	v_lshl_add_u64 v[22:23], v[22:23], 0, v[180:181]
	global_store_dwordx4 v[22:23], v[30:33], off
	v_pk_mul_f32 v[10:11], v[10:11], v[14:15]
	v_rcp_f32_e32 v16, v16
	v_pk_add_f32 v[6:7], v[6:7], 1.0 op_sel_hi:[1,0]
	v_rcp_f32_e32 v17, v17
	v_pk_mul_f32 v[4:5], v[4:5], v[234:235] op_sel_hi:[1,0]
	v_exp_f32_e32 v8, v8
	v_exp_f32_e32 v9, v9
	v_cvt_pk_bf16_f32 v14, v10, v11
	v_pk_mul_f32 v[12:13], v[12:13], v[16:17]
	v_rcp_f32_e32 v6, v6
	v_pk_add_f32 v[8:9], v[8:9], 1.0 op_sel_hi:[1,0]
	v_rcp_f32_e32 v7, v7
	v_cvt_pk_bf16_f32 v15, v12, v13
	v_pk_mul_f32 v[2:3], v[2:3], v[6:7]
	v_rcp_f32_e32 v8, v8
	v_rcp_f32_e32 v9, v9
	v_cvt_pk_bf16_f32 v16, v2, v3
	v_pk_mul_f32 v[4:5], v[4:5], v[8:9]
	v_cvt_pk_bf16_f32 v17, v4, v5
	v_mad_i64_i32 v[6:7], s[2:3], v146, s27, v[236:237]
	v_lshl_add_u64 v[6:7], v[6:7], 0, v[180:181]
	global_store_dwordx4 v[6:7], v[14:17], off
	s_setprio 0
	s_andn2_b64 vcc, exec, s[40:41]
	s_mov_b64 s[2:3], -1
	s_cbranch_vccnz .LBB0_162
	s_andn2_b64 vcc, exec, s[38:39]
	s_cbranch_vccnz .LBB0_161
	s_barrier
	s_branch .LBB0_161

;     DI void operator()(const f32x4 (&acc)[2][2][4][2], const pg8::Unit& u, int wr, int wc, int fr, int fq) const {
;         const int row0 = u.pm * 256 + wr * 64 + fr, col0 = u.pn * 128 + wc * 32 + 8 * fq;
;         float rs[2][4]; row_rstd(ssq, row0, fq, rs);
; #pragma unroll
;         for (int ai = 0; ai < 2; ++ai)
; #pragma unroll
;             for (int m = 0; m < 4; ++m) {
;                 typedef float f32x2 __attribute__((ext_vector_type(2)));
;                 const float r = rs[ai][m]; const float r2s = r * r, rls = r * -1.44269504f; const f32x2 r2 = {r2s, r2s}, rl = {rls, rls};
;                 unsigned hw[4];
; #pragma unroll
;                 for (int q = 0; q < 4; ++q) {
;                     const f32x4 gq = acc[ai][0][m][q >> 1], uq = acc[ai][1][m][q >> 1];
;                     const f32x2 g2 = {gq[2 * (q & 1)], gq[2 * (q & 1) + 1]}, u2 = {uq[2 * (q & 1)], uq[2 * (q & 1) + 1]};
;                     const f32x2 t = g2 * rl; f32x2 e; e.x = __builtin_amdgcn_exp2f(t.x); e.y = __builtin_amdgcn_exp2f(t.y);
;                     const f32x2 d = e + 1.0f; f32x2 rc; rc.x = __builtin_amdgcn_rcpf(d.x); rc.y = __builtin_amdgcn_rcpf(d.y);
;                     const f32x2 hv = ((g2 * u2) * r2) * rc;
.Lrc_skip_1:
.LBB0_1125:
	v_and_b32_e32 v131, 64, v194
	v_xor_b32_e32 v130, 16, v194
	v_add_u32_e32 v131, 64, v131
	v_cmp_lt_i32_e32 vcc, v130, v131
	v_lshl_add_u32 v160, s58, 8, v182
	v_ashrrev_i32_e32 v161, 31, v160
	v_cndmask_b32_e32 v130, v194, v130, vcc
	v_lshlrev_b32_e32 v186, 2, v130
	v_xor_b32_e32 v130, 32, v194
	v_cmp_lt_i32_e32 vcc, v130, v131
	v_or_b32_e32 v158, 16, v160
	v_ashrrev_i32_e32 v159, 31, v158
	v_cndmask_b32_e32 v130, v194, v130, vcc
	v_lshlrev_b32_e32 v163, 2, v130
	v_lshlrev_b64 v[130:131], 6, v[160:161]
	v_lshl_add_u64 v[130:131], v[140:141], 0, v[130:131]
	v_mov_b64_e32 v[178:179], s[16:17]
	v_or_b32_e32 v156, 32, v160
	v_ashrrev_i32_e32 v157, 31, v156
	v_or_b32_e32 v154, 48, v160
	v_ashrrev_i32_e32 v155, 31, v154
	v_add_u32_e32 v152, 0x80, v160
	v_ashrrev_i32_e32 v153, 31, v152
	v_add_u32_e32 v150, 0x90, v160
	v_ashrrev_i32_e32 v151, 31, v150
	v_pk_mul_f32 v[122:123], v[126:127], v[122:123]
	v_pk_mul_f32 v[124:125], v[128:129], v[124:125]
	v_pk_mul_f32 v[114:115], v[118:119], v[114:115]
	v_pk_mul_f32 v[116:117], v[120:121], v[116:117]
	v_lshl_or_b32 v162, s57, 7, v184
	v_pk_mul_f32 v[106:107], v[110:111], v[106:107]
	v_pk_mul_f32 v[108:109], v[112:113], v[108:109]
	v_pk_mul_f32 v[98:99], v[102:103], v[98:99]
	v_pk_mul_f32 v[100:101], v[104:105], v[100:101]
	v_pk_mul_f32 v[90:91], v[94:95], v[90:91]
	v_pk_mul_f32 v[92:93], v[96:97], v[92:93]
	v_pk_mul_f32 v[82:83], v[86:87], v[82:83]
	v_pk_mul_f32 v[84:85], v[88:89], v[84:85]
	v_pk_mul_f32 v[74:75], v[78:79], v[74:75]
	v_pk_mul_f32 v[76:77], v[80:81], v[76:77]
	v_pk_mul_f32 v[66:67], v[70:71], v[66:67]
	v_pk_mul_f32 v[68:69], v[72:73], v[68:69]
	v_pk_mul_f32 v[58:59], v[62:63], v[58:59]
	v_pk_mul_f32 v[60:61], v[64:65], v[60:61]
	v_pk_mul_f32 v[50:51], v[54:55], v[50:51]
	v_pk_mul_f32 v[52:53], v[56:57], v[52:53]
	v_pk_mul_f32 v[42:43], v[46:47], v[42:43]
	v_pk_mul_f32 v[44:45], v[48:49], v[44:45]
	v_pk_mul_f32 v[34:35], v[38:39], v[34:35]
	v_pk_mul_f32 v[36:37], v[40:41], v[36:37]
	v_pk_mul_f32 v[26:27], v[30:31], v[26:27]
	v_pk_mul_f32 v[28:29], v[32:33], v[28:29]
	v_pk_mul_f32 v[18:19], v[22:23], v[18:19]
	v_pk_mul_f32 v[20:21], v[24:25], v[20:21]
	v_pk_mul_f32 v[10:11], v[14:15], v[10:11]
	v_pk_mul_f32 v[12:13], v[16:17], v[12:13]
	v_pk_mul_f32 v[2:3], v[6:7], v[2:3]
	v_pk_mul_f32 v[4:5], v[8:9], v[4:5]
	s_and_b64 vcc, exec, s[44:45]
	s_cbranch_vccz .Lab_1
	s_barrier
	s_setprio 2

; DI unsigned pk2(float lo, float hi) { return pg8::cvt_pk_bf16(lo, hi); }
;     DI void operator()(const f32x4 (&acc)[2][2][4][2], const pg8::Unit& u, int wr, int wc, int fr, int fq) const {
;     ...
;                 const float r = rs[ai][m]; const float r2s = r * r, rls = r * -1.44269504f; const f32x2 r2 = {r2s, r2s}, rl = {rls, rls};
;                 unsigned hw[4];
; #pragma unroll
;                 for (int q = 0; q < 4; ++q) {
;                     const f32x4 gq = acc[ai][0][m][q >> 1], uq = acc[ai][1][m][q >> 1];
;                     const f32x2 g2 = {gq[2 * (q & 1)], gq[2 * (q & 1) + 1]}, u2 = {uq[2 * (q & 1)], uq[2 * (q & 1) + 1]};
;                     const f32x2 t = g2 * rl; f32x2 e; e.x = __builtin_amdgcn_exp2f(t.x); e.y = __builtin_amdgcn_exp2f(t.y);
;                     const f32x2 d = e + 1.0f; f32x2 rc; rc.x = __builtin_amdgcn_rcpf(d.x); rc.y = __builtin_amdgcn_rcpf(d.y);
;                     const f32x2 hv = ((g2 * u2) * r2) * rc;
;                     hw[q] = pk2(hv.x, hv.y);
;                 }
;                 u32x4 w; w.x = hw[0]; w.y = hw[1]; w.z = hw[2]; w.w = hw[3];
;                 *(u32x4*)(H + (size_t)(row0 + ai * 128 + m * 16) * DFF + col0) = w;
.Lrc_done_1:
	v_mov_b64_e32 v[236:237], s[84:85]
	v_lshlrev_b64 v[180:181], 1, v[162:163]
	v_mul_f32_e32 v178, 0xbfb8aa3b, v161
	v_pk_mul_f32 v[126:127], v[126:127], v[178:179] op_sel_hi:[1,0]
	v_mul_f32_e32 v132, v161, v161
	v_pk_mul_f32 v[122:123], v[122:123], v[132:133] op_sel_hi:[1,0]
	v_exp_f32_e32 v126, v126
	v_pk_mul_f32 v[128:129], v[128:129], v[178:179] op_sel_hi:[1,0]
	v_exp_f32_e32 v127, v127
	s_nop 0
	v_pk_add_f32 v[126:127], v[126:127], 1.0 op_sel_hi:[1,0]
	v_pk_mul_f32 v[124:125], v[124:125], v[132:133] op_sel_hi:[1,0]
	v_exp_f32_e32 v128, v128
	v_pk_mul_f32 v[118:119], v[118:119], v[178:179] op_sel_hi:[1,0]
	v_exp_f32_e32 v129, v129
	v_rcp_f32_e32 v126, v126
	v_pk_add_f32 v[128:129], v[128:129], 1.0 op_sel_hi:[1,0]
	v_rcp_f32_e32 v127, v127
	v_pk_mul_f32 v[114:115], v[114:115], v[132:133] op_sel_hi:[1,0]
	v_exp_f32_e32 v118, v118
	v_pk_mul_f32 v[120:121], v[120:121], v[178:179] op_sel_hi:[1,0]
	v_exp_f32_e32 v119, v119
	v_pk_mul_f32 v[122:123], v[122:123], v[126:127]
	v_rcp_f32_e32 v128, v128
	v_pk_add_f32 v[118:119], v[118:119], 1.0 op_sel_hi:[1,0]
	v_rcp_f32_e32 v129, v129
	v_pk_mul_f32 v[116:117], v[116:117], v[132:133] op_sel_hi:[1,0]
	v_exp_f32_e32 v120, v120
	v_mul_f32_e32 v190, 0xbfb8aa3b, v159
	v_pk_mul_f32 v[110:111], v[110:111], v[190:191] op_sel_hi:[1,0]
	v_exp_f32_e32 v121, v121
	v_cvt_pk_bf16_f32 v126, v122, v123
	v_pk_mul_f32 v[124:125], v[124:125], v[128:129]
	v_rcp_f32_e32 v118, v118
	v_pk_add_f32 v[120:121], v[120:121], 1.0 op_sel_hi:[1,0]
	v_rcp_f32_e32 v119, v119
	v_mul_f32_e32 v234, v159, v159
	v_pk_mul_f32 v[106:107], v[106:107], v[234:235] op_sel_hi:[1,0]
	v_exp_f32_e32 v110, v110
	v_pk_mul_f32 v[112:113], v[112:113], v[190:191] op_sel_hi:[1,0]
	v_exp_f32_e32 v111, v111
	v_cvt_pk_bf16_f32 v127, v124, v125
	v_pk_mul_f32 v[114:115], v[114:115], v[118:119]
	v_rcp_f32_e32 v120, v120
	v_pk_add_f32 v[110:111], v[110:111], 1.0 op_sel_hi:[1,0]
	v_rcp_f32_e32 v121, v121
	v_pk_mul_f32 v[108:109], v[108:109], v[234:235] op_sel_hi:[1,0]
	v_exp_f32_e32 v112, v112
	v_pk_mul_f32 v[102:103], v[102:103], v[190:191] op_sel_hi:[1,0]
	v_exp_f32_e32 v113, v113
	v_cvt_pk_bf16_f32 v128, v114, v115
	v_pk_mul_f32 v[116:117], v[116:117], v[120:121]
	v_rcp_f32_e32 v110, v110
	v_pk_add_f32 v[112:113], v[112:113], 1.0 op_sel_hi:[1,0]
	v_rcp_f32_e32 v111, v111
	v_pk_mul_f32 v[98:99], v[98:99], v[234:235] op_sel_hi:[1,0]
	v_exp_f32_e32 v102, v102
	v_pk_mul_f32 v[104:105], v[104:105], v[190:191] op_sel_hi:[1,0]
	v_exp_f32_e32 v103, v103
	v_cvt_pk_bf16_f32 v129, v116, v117
	v_mad_i64_i32 v[118:119], s[2:3], v160, s27, v[236:237]
	v_lshl_add_u64 v[118:119], v[118:119], 0, v[180:181]
	global_store_dwordx4 v[118:119], v[126:129], off
	v_pk_mul_f32 v[106:107], v[106:107], v[110:111]
	v_rcp_f32_e32 v112, v112
	v_pk_add_f32 v[102:103], v[102:103], 1.0 op_sel_hi:[1,0]
	v_rcp_f32_e32 v113, v113
	v_pk_mul_f32 v[100:101], v[100:101], v[234:235] op_sel_hi:[1,0]
	v_exp_f32_e32 v104, v104
	v_mul_f32_e32 v178, 0xbfb8aa3b, v157
	v_pk_mul_f32 v[94:95], v[94:95], v[178:179] op_sel_hi:[1,0]
	v_exp_f32_e32 v105, v105
	v_cvt_pk_bf16_f32 v110, v106, v107
	v_pk_mul_f32 v[108:109], v[108:109], v[112:113]
	v_rcp_f32_e32 v102, v102
	v_pk_add_f32 v[104:105], v[104:105], 1.0 op_sel_hi:[1,0]
	v_rcp_f32_e32 v103, v103
	v_mul_f32_e32 v132, v157, v157
	v_pk_mul_f32 v[90:91], v[90:91], v[132:133] op_sel_hi:[1,0]
	v_exp_f32_e32 v94, v94
	v_pk_mul_f32 v[96:97], v[96:97], v[178:179] op_sel_hi:[1,0]
	v_exp_f32_e32 v95, v95
	v_cvt_pk_bf16_f32 v111, v108, v109
	v_pk_mul_f32 v[98:99], v[98:99], v[102:103]
	v_rcp_f32_e32 v104, v104
	v_pk_add_f32 v[94:95], v[94:95], 1.0 op_sel_hi:[1,0]
	v_rcp_f32_e32 v105, v105
	v_pk_mul_f32 v[92:93], v[92:93], v[132:133] op_sel_hi:[1,0]
	v_exp_f32_e32 v96, v96
	v_pk_mul_f32 v[86:87], v[86:87], v[178:179] op_sel_hi:[1,0]
	v_exp_f32_e32 v97, v97
	v_cvt_pk_bf16_f32 v112, v98, v99
	v_pk_mul_f32 v[100:101], v[100:101], v[104:105]
	v_rcp_f32_e32 v94, v94
	v_pk_add_f32 v[96:97], v[96:97], 1.0 op_sel_hi:[1,0]
	v_rcp_f32_e32 v95, v95
	v_pk_mul_f32 v[82:83], v[82:83], v[132:133] op_sel_hi:[1,0]
	v_exp_f32_e32 v86, v86
	v_pk_mul_f32 v[88:89], v[88:89], v[178:179] op_sel_hi:[1,0]
	v_exp_f32_e32 v87, v87
	v_cvt_pk_bf16_f32 v113, v100, v101
	v_mad_i64_i32 v[102:103], s[2:3], v158, s27, v[236:237]
	v_lshl_add_u64 v[102:103], v[102:103], 0, v[180:181]
	global_store_dwordx4 v[102:103], v[110:113], off
	v_pk_mul_f32 v[90:91], v[90:91], v[94:95]
	v_rcp_f32_e32 v96, v96
	v_pk_add_f32 v[86:87], v[86:87], 1.0 op_sel_hi:[1,0]
	v_rcp_f32_e32 v97, v97
	v_pk_mul_f32 v[84:85], v[84:85], v[132:133] op_sel_hi:[1,0]
	v_exp_f32_e32 v88, v88
	v_mul_f32_e32 v190, 0xbfb8aa3b, v155
	v_pk_mul_f32 v[78:79], v[78:79], v[190:191] op_sel_hi:[1,0]
	v_exp_f32_e32 v89, v89
	v_cvt_pk_bf16_f32 v94, v90, v91
	v_pk_mul_f32 v[92:93], v[92:93], v[96:97]
	v_rcp_f32_e32 v86, v86
	v_pk_add_f32 v[88:89], v[88:89], 1.0 op_sel_hi:[1,0]
	v_rcp_f32_e32 v87, v87
	v_mul_f32_e32 v234, v155, v155
	v_pk_mul_f32 v[74:75], v[74:75], v[234:235] op_sel_hi:[1,0]
	v_exp_f32_e32 v78, v78
	v_pk_mul_f32 v[80:81], v[80:81], v[190:191] op_sel_hi:[1,0]
	v_exp_f32_e32 v79, v79
	v_cvt_pk_bf16_f32 v95, v92, v93
	v_pk_mul_f32 v[82:83], v[82:83], v[86:87]
	v_rcp_f32_e32 v88, v88
	v_pk_add_f32 v[78:79], v[78:79], 1.0 op_sel_hi:[1,0]
	v_rcp_f32_e32 v89, v89
	v_pk_mul_f32 v[76:77], v[76:77], v[234:235] op_sel_hi:[1,0]
	v_exp_f32_e32 v80, v80
	v_pk_mul_f32 v[70:71], v[70:71], v[190:191] op_sel_hi:[1,0]
	v_exp_f32_e32 v81, v81
	v_cvt_pk_bf16_f32 v96, v82, v83
	v_pk_mul_f32 v[84:85], v[84:85], v[88:89]
	v_rcp_f32_e32 v78, v78
	v_pk_add_f32 v[80:81], v[80:81], 1.0 op_sel_hi:[1,0]
	v_rcp_f32_e32 v79, v79
; DI unsigned pk2(float lo, float hi) { return pg8::cvt_pk_bf16(lo, hi); }
;     DI void operator()(const f32x4 (&acc)[2][2][4][2], const pg8::Unit& u, int wr, int wc, int fr, int fq) const {
;     ...
;                 const float r = rs[ai][m]; const float r2s = r * r, rls = r * -1.44269504f; const f32x2 r2 = {r2s, r2s}, rl = {rls, rls};
;                 unsigned hw[4];
; #pragma unroll
;                 for (int q = 0; q < 4; ++q) {
;                     const f32x4 gq = acc[ai][0][m][q >> 1], uq = acc[ai][1][m][q >> 1];
;                     const f32x2 g2 = {gq[2 * (q & 1)], gq[2 * (q & 1) + 1]}, u2 = {uq[2 * (q & 1)], uq[2 * (q & 1) + 1]};
;                     const f32x2 t = g2 * rl; f32x2 e; e.x = __builtin_amdgcn_exp2f(t.x); e.y = __builtin_amdgcn_exp2f(t.y);
;                     const f32x2 d = e + 1.0f; f32x2 rc; rc.x = __builtin_amdgcn_rcpf(d.x); rc.y = __builtin_amdgcn_rcpf(d.y);
;                     const f32x2 hv = ((g2 * u2) * r2) * rc;
;                     hw[q] = pk2(hv.x, hv.y);
;                 }
;                 u32x4 w; w.x = hw[0]; w.y = hw[1]; w.z = hw[2]; w.w = hw[3];
;                 *(u32x4*)(H + (size_t)(row0 + ai * 128 + m * 16) * DFF + col0) = w;
	v_pk_mul_f32 v[66:67], v[66:67], v[234:235] op_sel_hi:[1,0]
	v_exp_f32_e32 v70, v70
	v_pk_mul_f32 v[72:73], v[72:73], v[190:191] op_sel_hi:[1,0]
	v_exp_f32_e32 v71, v71
	v_cvt_pk_bf16_f32 v97, v84, v85
	v_mad_i64_i32 v[86:87], s[2:3], v156, s27, v[236:237]
	v_lshl_add_u64 v[86:87], v[86:87], 0, v[180:181]
	global_store_dwordx4 v[86:87], v[94:97], off
	v_pk_mul_f32 v[74:75], v[74:75], v[78:79]
	v_rcp_f32_e32 v80, v80
	v_pk_add_f32 v[70:71], v[70:71], 1.0 op_sel_hi:[1,0]
	v_rcp_f32_e32 v81, v81
	v_pk_mul_f32 v[68:69], v[68:69], v[234:235] op_sel_hi:[1,0]
	v_exp_f32_e32 v72, v72
	v_mul_f32_e32 v178, 0xbfb8aa3b, v153
	v_pk_mul_f32 v[62:63], v[62:63], v[178:179] op_sel_hi:[1,0]
	v_exp_f32_e32 v73, v73
	v_cvt_pk_bf16_f32 v78, v74, v75
	v_pk_mul_f32 v[76:77], v[76:77], v[80:81]
	v_rcp_f32_e32 v70, v70
	v_pk_add_f32 v[72:73], v[72:73], 1.0 op_sel_hi:[1,0]
	v_rcp_f32_e32 v71, v71
	v_mul_f32_e32 v132, v153, v153
	v_pk_mul_f32 v[58:59], v[58:59], v[132:133] op_sel_hi:[1,0]
	v_exp_f32_e32 v62, v62
	v_pk_mul_f32 v[64:65], v[64:65], v[178:179] op_sel_hi:[1,0]
	v_exp_f32_e32 v63, v63
	v_cvt_pk_bf16_f32 v79, v76, v77
	v_pk_mul_f32 v[66:67], v[66:67], v[70:71]
	v_rcp_f32_e32 v72, v72
	v_pk_add_f32 v[62:63], v[62:63], 1.0 op_sel_hi:[1,0]
	v_rcp_f32_e32 v73, v73
	v_pk_mul_f32 v[60:61], v[60:61], v[132:133] op_sel_hi:[1,0]
	v_exp_f32_e32 v64, v64
	v_pk_mul_f32 v[54:55], v[54:55], v[178:179] op_sel_hi:[1,0]
	v_exp_f32_e32 v65, v65
	v_cvt_pk_bf16_f32 v80, v66, v67
	v_pk_mul_f32 v[68:69], v[68:69], v[72:73]
	v_rcp_f32_e32 v62, v62
	v_pk_add_f32 v[64:65], v[64:65], 1.0 op_sel_hi:[1,0]
	v_rcp_f32_e32 v63, v63
	v_pk_mul_f32 v[50:51], v[50:51], v[132:133] op_sel_hi:[1,0]
	v_exp_f32_e32 v54, v54
	v_pk_mul_f32 v[56:57], v[56:57], v[178:179] op_sel_hi:[1,0]
	v_exp_f32_e32 v55, v55
	v_cvt_pk_bf16_f32 v81, v68, v69
	v_mad_i64_i32 v[70:71], s[2:3], v154, s27, v[236:237]
	v_lshl_add_u64 v[70:71], v[70:71], 0, v[180:181]
	global_store_dwordx4 v[70:71], v[78:81], off
	v_pk_mul_f32 v[58:59], v[58:59], v[62:63]
	v_rcp_f32_e32 v64, v64
	v_pk_add_f32 v[54:55], v[54:55], 1.0 op_sel_hi:[1,0]
	v_rcp_f32_e32 v65, v65
	v_pk_mul_f32 v[52:53], v[52:53], v[132:133] op_sel_hi:[1,0]
	v_exp_f32_e32 v56, v56
	v_mul_f32_e32 v190, 0xbfb8aa3b, v151
	v_pk_mul_f32 v[46:47], v[46:47], v[190:191] op_sel_hi:[1,0]
	v_exp_f32_e32 v57, v57
	v_cvt_pk_bf16_f32 v62, v58, v59
	v_pk_mul_f32 v[60:61], v[60:61], v[64:65]
	v_rcp_f32_e32 v54, v54
	v_pk_add_f32 v[56:57], v[56:57], 1.0 op_sel_hi:[1,0]
	v_rcp_f32_e32 v55, v55
	v_mul_f32_e32 v234, v151, v151
	v_pk_mul_f32 v[42:43], v[42:43], v[234:235] op_sel_hi:[1,0]
	v_exp_f32_e32 v46, v46
	v_pk_mul_f32 v[48:49], v[48:49], v[190:191] op_sel_hi:[1,0]
	v_exp_f32_e32 v47, v47
	v_cvt_pk_bf16_f32 v63, v60, v61
	v_pk_mul_f32 v[50:51], v[50:51], v[54:55]
	v_rcp_f32_e32 v56, v56
	v_pk_add_f32 v[46:47], v[46:47], 1.0 op_sel_hi:[1,0]
	v_rcp_f32_e32 v57, v57
	v_pk_mul_f32 v[44:45], v[44:45], v[234:235] op_sel_hi:[1,0]
	v_exp_f32_e32 v48, v48
	v_pk_mul_f32 v[38:39], v[38:39], v[190:191] op_sel_hi:[1,0]
	v_exp_f32_e32 v49, v49
	v_cvt_pk_bf16_f32 v64, v50, v51
	v_pk_mul_f32 v[52:53], v[52:53], v[56:57]
	v_rcp_f32_e32 v46, v46
	v_pk_add_f32 v[48:49], v[48:49], 1.0 op_sel_hi:[1,0]
	v_rcp_f32_e32 v47, v47
	v_pk_mul_f32 v[34:35], v[34:35], v[234:235] op_sel_hi:[1,0]
	v_exp_f32_e32 v38, v38
	v_pk_mul_f32 v[40:41], v[40:41], v[190:191] op_sel_hi:[1,0]
	v_exp_f32_e32 v39, v39
	v_cvt_pk_bf16_f32 v65, v52, v53
	v_mad_i64_i32 v[54:55], s[2:3], v152, s27, v[236:237]
	v_lshl_add_u64 v[54:55], v[54:55], 0, v[180:181]
	global_store_dwordx4 v[54:55], v[62:65], off
	v_pk_mul_f32 v[42:43], v[42:43], v[46:47]
	v_rcp_f32_e32 v48, v48
	v_pk_add_f32 v[38:39], v[38:39], 1.0 op_sel_hi:[1,0]
	v_rcp_f32_e32 v49, v49
	v_pk_mul_f32 v[36:37], v[36:37], v[234:235] op_sel_hi:[1,0]
	v_exp_f32_e32 v40, v40
	v_mul_f32_e32 v178, 0xbfb8aa3b, v131
; #define PG8_BAR __builtin_amdgcn_s_barrier()
; DI unsigned pk2(float lo, float hi) { return pg8::cvt_pk_bf16(lo, hi); }
; template <class Epi, class Sched, bool ALIGN_EPI = false, bool SP2 = false>
; __device__ __forceinline__ void gemm_phase(PG8_LAS unsigned char* lds, const Gemm g, const Sched& S, const Epi& E) {
;     ...
;         if (!has_next) break;
; #pragma unroll
;         for (int a = 0; a < 2; ++a)
; #pragma unroll
;             for (int b = 0; b < 2; ++b)
; #pragma unroll
;                 for (int m = 0; m < 4; ++m)
; #pragma unroll
;                     for (int n = 0; n < 2; ++n) acc[a][b][m][n] = (f32x4){0.f, 0.f, 0.f, 0.f};
;         cur = nxt; cA = nA; cB = nB; ++ui;
;         if constexpr (ALIGN_EPI) { if (wr == 1) PG8_BAR; }
;     DI void operator()(const f32x4 (&acc)[2][2][4][2], const pg8::Unit& u, int wr, int wc, int fr, int fq) const {
;     ...
;                 const float r = rs[ai][m]; const float r2s = r * r, rls = r * -1.44269504f; const f32x2 r2 = {r2s, r2s}, rl = {rls, rls};
;                 unsigned hw[4];
; #pragma unroll
;                 for (int q = 0; q < 4; ++q) {
;                     const f32x4 gq = acc[ai][0][m][q >> 1], uq = acc[ai][1][m][q >> 1];
;                     const f32x2 g2 = {gq[2 * (q & 1)], gq[2 * (q & 1) + 1]}, u2 = {uq[2 * (q & 1)], uq[2 * (q & 1) + 1]};
;                     const f32x2 t = g2 * rl; f32x2 e; e.x = __builtin_amdgcn_exp2f(t.x); e.y = __builtin_amdgcn_exp2f(t.y);
;                     const f32x2 d = e + 1.0f; f32x2 rc; rc.x = __builtin_amdgcn_rcpf(d.x); rc.y = __builtin_amdgcn_rcpf(d.y);
;                     const f32x2 hv = ((g2 * u2) * r2) * rc;
;                     hw[q] = pk2(hv.x, hv.y);
;                 }
;                 u32x4 w; w.x = hw[0]; w.y = hw[1]; w.z = hw[2]; w.w = hw[3];
;                 *(u32x4*)(H + (size_t)(row0 + ai * 128 + m * 16) * DFF + col0) = w;
	v_pk_mul_f32 v[30:31], v[30:31], v[178:179] op_sel_hi:[1,0]
	v_exp_f32_e32 v41, v41
	v_cvt_pk_bf16_f32 v46, v42, v43
	v_pk_mul_f32 v[44:45], v[44:45], v[48:49]
	v_rcp_f32_e32 v38, v38
	v_pk_add_f32 v[40:41], v[40:41], 1.0 op_sel_hi:[1,0]
	v_rcp_f32_e32 v39, v39
	v_mul_f32_e32 v132, v131, v131
	v_pk_mul_f32 v[26:27], v[26:27], v[132:133] op_sel_hi:[1,0]
	v_exp_f32_e32 v30, v30
	v_pk_mul_f32 v[32:33], v[32:33], v[178:179] op_sel_hi:[1,0]
	v_exp_f32_e32 v31, v31
	v_cvt_pk_bf16_f32 v47, v44, v45
	v_pk_mul_f32 v[34:35], v[34:35], v[38:39]
	v_rcp_f32_e32 v40, v40
	v_pk_add_f32 v[30:31], v[30:31], 1.0 op_sel_hi:[1,0]
	v_rcp_f32_e32 v41, v41
	v_pk_mul_f32 v[28:29], v[28:29], v[132:133] op_sel_hi:[1,0]
	v_exp_f32_e32 v32, v32
	v_pk_mul_f32 v[22:23], v[22:23], v[178:179] op_sel_hi:[1,0]
	v_exp_f32_e32 v33, v33
	v_cvt_pk_bf16_f32 v48, v34, v35
	v_pk_mul_f32 v[36:37], v[36:37], v[40:41]
	v_rcp_f32_e32 v30, v30
	v_pk_add_f32 v[32:33], v[32:33], 1.0 op_sel_hi:[1,0]
	v_rcp_f32_e32 v31, v31
	v_pk_mul_f32 v[18:19], v[18:19], v[132:133] op_sel_hi:[1,0]
	v_exp_f32_e32 v22, v22
	v_pk_mul_f32 v[24:25], v[24:25], v[178:179] op_sel_hi:[1,0]
	v_exp_f32_e32 v23, v23
	v_cvt_pk_bf16_f32 v49, v36, v37
	v_mad_i64_i32 v[38:39], s[2:3], v150, s27, v[236:237]
	v_lshl_add_u64 v[38:39], v[38:39], 0, v[180:181]
	global_store_dwordx4 v[38:39], v[46:49], off
	v_pk_mul_f32 v[26:27], v[26:27], v[30:31]
	v_rcp_f32_e32 v32, v32
	v_pk_add_f32 v[22:23], v[22:23], 1.0 op_sel_hi:[1,0]
	v_rcp_f32_e32 v33, v33
	v_pk_mul_f32 v[20:21], v[20:21], v[132:133] op_sel_hi:[1,0]
	v_exp_f32_e32 v24, v24
	v_mul_f32_e32 v190, 0xbfb8aa3b, v130
	v_pk_mul_f32 v[14:15], v[14:15], v[190:191] op_sel_hi:[1,0]
	v_exp_f32_e32 v25, v25
	v_cvt_pk_bf16_f32 v30, v26, v27
	v_pk_mul_f32 v[28:29], v[28:29], v[32:33]
	v_rcp_f32_e32 v22, v22
	v_pk_add_f32 v[24:25], v[24:25], 1.0 op_sel_hi:[1,0]
	v_rcp_f32_e32 v23, v23
	v_mul_f32_e32 v234, v130, v130
	v_pk_mul_f32 v[10:11], v[10:11], v[234:235] op_sel_hi:[1,0]
	v_exp_f32_e32 v14, v14
	v_pk_mul_f32 v[16:17], v[16:17], v[190:191] op_sel_hi:[1,0]
	v_exp_f32_e32 v15, v15
	v_cvt_pk_bf16_f32 v31, v28, v29
	v_pk_mul_f32 v[18:19], v[18:19], v[22:23]
	v_rcp_f32_e32 v24, v24
	v_pk_add_f32 v[14:15], v[14:15], 1.0 op_sel_hi:[1,0]
	v_rcp_f32_e32 v25, v25
	v_pk_mul_f32 v[12:13], v[12:13], v[234:235] op_sel_hi:[1,0]
	v_exp_f32_e32 v16, v16
	v_pk_mul_f32 v[6:7], v[6:7], v[190:191] op_sel_hi:[1,0]
	v_exp_f32_e32 v17, v17
	v_cvt_pk_bf16_f32 v32, v18, v19
	v_pk_mul_f32 v[20:21], v[20:21], v[24:25]
	v_rcp_f32_e32 v14, v14
	v_pk_add_f32 v[16:17], v[16:17], 1.0 op_sel_hi:[1,0]
	v_rcp_f32_e32 v15, v15
	v_pk_mul_f32 v[2:3], v[2:3], v[234:235] op_sel_hi:[1,0]
	v_exp_f32_e32 v6, v6
	v_pk_mul_f32 v[8:9], v[8:9], v[190:191] op_sel_hi:[1,0]
	v_exp_f32_e32 v7, v7
	v_cvt_pk_bf16_f32 v33, v20, v21
	v_mad_i64_i32 v[22:23], s[2:3], v148, s27, v[236:237]
	v_lshl_add_u64 v[22:23], v[22:23], 0, v[180:181]
	global_store_dwordx4 v[22:23], v[30:33], off
	v_pk_mul_f32 v[10:11], v[10:11], v[14:15]
	v_rcp_f32_e32 v16, v16
	v_pk_add_f32 v[6:7], v[6:7], 1.0 op_sel_hi:[1,0]
	v_rcp_f32_e32 v17, v17
	v_pk_mul_f32 v[4:5], v[4:5], v[234:235] op_sel_hi:[1,0]
	v_exp_f32_e32 v8, v8
	v_exp_f32_e32 v9, v9
	v_cvt_pk_bf16_f32 v14, v10, v11
	v_pk_mul_f32 v[12:13], v[12:13], v[16:17]
	v_rcp_f32_e32 v6, v6
	v_pk_add_f32 v[8:9], v[8:9], 1.0 op_sel_hi:[1,0]
	v_rcp_f32_e32 v7, v7
	v_cvt_pk_bf16_f32 v15, v12, v13
	v_pk_mul_f32 v[2:3], v[2:3], v[6:7]
	v_rcp_f32_e32 v8, v8
	v_rcp_f32_e32 v9, v9
	v_cvt_pk_bf16_f32 v16, v2, v3
	v_pk_mul_f32 v[4:5], v[4:5], v[8:9]
	v_cvt_pk_bf16_f32 v17, v4, v5
	v_mad_i64_i32 v[6:7], s[2:3], v146, s27, v[236:237]
	v_lshl_add_u64 v[6:7], v[6:7], 0, v[180:181]
	global_store_dwordx4 v[6:7], v[14:17], off
	s_setprio 0
	s_andn2_b64 vcc, exec, s[38:39]
	s_mov_b64 s[2:3], -1
	s_cbranch_vccnz .LBB0_1118
	s_andn2_b64 vcc, exec, s[42:43]
	s_cbranch_vccnz .LBB0_1117
	s_barrier
	s_branch .LBB0_1117
